# grid barrier: non-leader workgroups poll the top-level generation word directly (skip per-XCD release hop), on top of v022
# speedup vs baseline: 1.0019x; 1.0019x over previous
.LBB0_141:
	s_or_b64 exec, exec, s[8:9]
	v_cvt_f32_u32_e32 v4, v2
	s_waitcnt vmcnt(0)
	v_readfirstlane_b32 s6, v3
	v_sub_u32_e32 v3, 0, v2
	v_rcp_iflag_f32_e32 v4, v4
	v_add_u32_e32 v5, s6, v1
	v_mul_f32_e32 v4, 0x4f7ffffe, v4
	v_cvt_u32_f32_e32 v4, v4
	v_mul_lo_u32 v1, v3, v4
	v_mul_hi_u32 v1, v4, v1
	v_add_u32_e32 v1, v4, v1
	v_mul_hi_u32 v1, v5, v1
	v_mul_lo_u32 v3, v1, v2
	v_sub_u32_e32 v3, v5, v3
	v_add_u32_e32 v4, 1, v1
	v_cmp_ge_u32_e32 vcc, v3, v2
	s_nop 1
	v_cndmask_b32_e32 v1, v1, v4, vcc
	v_sub_u32_e32 v4, v3, v2
	v_cndmask_b32_e32 v3, v3, v4, vcc
	v_add_u32_e32 v4, 1, v1
	v_cmp_ge_u32_e32 vcc, v3, v2
	v_add_u32_e32 v3, 1, v5
	s_nop 0
	v_cndmask_b32_e32 v1, v1, v4, vcc
	v_mul_lo_u32 v4, v2, v1
	v_add_u32_e32 v2, v4, v2
	v_cmp_ne_u32_e32 vcc, v3, v2
	s_and_saveexec_b64 s[6:7], vcc
	s_xor_b64 s[6:7], exec, s[6:7]
	s_cbranch_execz .LBB0_155
	s_waitcnt lgkmcnt(0)
	v_mov_b32_e32 v0, 0x7100
	global_load_dword v0, v0, s[40:41] offset:1024 sc1
	s_add_u32 s12, s40, 0x7500
	s_addc_u32 s13, s41, 0
	s_waitcnt vmcnt(0)
	v_cmp_eq_u32_e32 vcc, v0, v1
	s_and_saveexec_b64 s[8:9], vcc
	s_cbranch_execz .LBB0_154
	s_add_u32 s10, s40, 0x4200
	s_addc_u32 s11, s41, 0
	s_mov_b32 s44, 1
	s_mov_b64 s[18:19], 0
	v_mov_b32_e32 v0, 0
	s_branch .LBB0_145

.LBB0_209:
	s_or_b64 exec, exec, s[8:9]
	v_cvt_f32_u32_e32 v4, v2
	s_waitcnt vmcnt(0)
	v_readfirstlane_b32 s6, v3
	v_sub_u32_e32 v3, 0, v2
	v_rcp_iflag_f32_e32 v4, v4
	v_add_u32_e32 v5, s6, v1
	v_mul_f32_e32 v4, 0x4f7ffffe, v4
	v_cvt_u32_f32_e32 v4, v4
	v_mul_lo_u32 v1, v3, v4
	v_mul_hi_u32 v1, v4, v1
	v_add_u32_e32 v1, v4, v1
	v_mul_hi_u32 v1, v5, v1
	v_mul_lo_u32 v3, v1, v2
	v_sub_u32_e32 v3, v5, v3
	v_add_u32_e32 v4, 1, v1
	v_cmp_ge_u32_e32 vcc, v3, v2
	s_nop 1
	v_cndmask_b32_e32 v1, v1, v4, vcc
	v_sub_u32_e32 v4, v3, v2
	v_cndmask_b32_e32 v3, v3, v4, vcc
	v_add_u32_e32 v4, 1, v1
	v_cmp_ge_u32_e32 vcc, v3, v2
	v_add_u32_e32 v3, 1, v5
	s_nop 0
	v_cndmask_b32_e32 v1, v1, v4, vcc
	v_mul_lo_u32 v4, v2, v1
	v_add_u32_e32 v2, v4, v2
	v_cmp_ne_u32_e32 vcc, v3, v2
	s_and_saveexec_b64 s[6:7], vcc
	s_xor_b64 s[6:7], exec, s[6:7]
	s_cbranch_execz .LBB0_223
	s_waitcnt lgkmcnt(0)
	v_mov_b32_e32 v0, 0x7100
	global_load_dword v0, v0, s[40:41] offset:1024 sc1
	s_add_u32 s12, s40, 0x7500
	s_addc_u32 s13, s41, 0
	s_waitcnt vmcnt(0)
	v_cmp_eq_u32_e32 vcc, v0, v1
	s_and_saveexec_b64 s[8:9], vcc
	s_cbranch_execz .LBB0_222
	s_add_u32 s10, s40, 0x4200
	s_addc_u32 s11, s41, 0
	s_mov_b32 s48, 1
	s_mov_b64 s[24:25], 0
	v_mov_b32_e32 v0, 0
	s_branch .LBB0_213

.LBB0_289:
	s_or_b64 exec, exec, s[8:9]
	v_cvt_f32_u32_e32 v4, v2
	s_waitcnt vmcnt(0)
	v_readfirstlane_b32 s6, v3
	v_sub_u32_e32 v3, 0, v2
	v_rcp_iflag_f32_e32 v4, v4
	v_add_u32_e32 v5, s6, v1
	v_mul_f32_e32 v4, 0x4f7ffffe, v4
	v_cvt_u32_f32_e32 v4, v4
	v_mul_lo_u32 v1, v3, v4
	v_mul_hi_u32 v1, v4, v1
	v_add_u32_e32 v1, v4, v1
	v_mul_hi_u32 v1, v5, v1
	v_mul_lo_u32 v3, v1, v2
	v_sub_u32_e32 v3, v5, v3
	v_add_u32_e32 v4, 1, v1
	v_cmp_ge_u32_e32 vcc, v3, v2
	s_nop 1
	v_cndmask_b32_e32 v1, v1, v4, vcc
	v_sub_u32_e32 v4, v3, v2
	v_cndmask_b32_e32 v3, v3, v4, vcc
	v_add_u32_e32 v4, 1, v1
	v_cmp_ge_u32_e32 vcc, v3, v2
	v_add_u32_e32 v3, 1, v5
	s_nop 0
	v_cndmask_b32_e32 v1, v1, v4, vcc
	v_mul_lo_u32 v4, v2, v1
	v_add_u32_e32 v2, v4, v2
	v_cmp_ne_u32_e32 vcc, v3, v2
	s_and_saveexec_b64 s[6:7], vcc
	s_xor_b64 s[6:7], exec, s[6:7]
	s_cbranch_execz .LBB0_303
	s_waitcnt lgkmcnt(0)
	v_mov_b32_e32 v0, 0x7100
	global_load_dword v0, v0, s[40:41] offset:1024 sc1
	s_add_u32 s30, s40, 0x7500
	s_addc_u32 s31, s41, 0
	s_waitcnt vmcnt(0)
	v_cmp_eq_u32_e32 vcc, v0, v1
	s_and_saveexec_b64 s[8:9], vcc
	s_cbranch_execz .LBB0_302
	s_add_u32 s10, s40, 0x4200
	s_addc_u32 s11, s41, 0
	s_mov_b32 s54, 1
	s_mov_b64 s[36:37], 0
	v_mov_b32_e32 v0, 0
	s_branch .LBB0_293

.LBB0_344:
	s_or_b64 exec, exec, s[8:9]
	v_cvt_f32_u32_e32 v4, v2
	s_waitcnt vmcnt(0)
	v_readfirstlane_b32 s6, v3
	v_sub_u32_e32 v3, 0, v2
	v_rcp_iflag_f32_e32 v4, v4
	v_add_u32_e32 v5, s6, v1
	v_mul_f32_e32 v4, 0x4f7ffffe, v4
	v_cvt_u32_f32_e32 v4, v4
	v_mul_lo_u32 v1, v3, v4
	v_mul_hi_u32 v1, v4, v1
	v_add_u32_e32 v1, v4, v1
	v_mul_hi_u32 v1, v5, v1
	v_mul_lo_u32 v3, v1, v2
	v_sub_u32_e32 v3, v5, v3
	v_add_u32_e32 v4, 1, v1
	v_cmp_ge_u32_e32 vcc, v3, v2
	s_nop 1
	v_cndmask_b32_e32 v1, v1, v4, vcc
	v_sub_u32_e32 v4, v3, v2
	v_cndmask_b32_e32 v3, v3, v4, vcc
	v_add_u32_e32 v4, 1, v1
	v_cmp_ge_u32_e32 vcc, v3, v2
	v_add_u32_e32 v3, 1, v5
	s_nop 0
	v_cndmask_b32_e32 v1, v1, v4, vcc
	v_mul_lo_u32 v4, v2, v1
	v_add_u32_e32 v2, v4, v2
	v_cmp_ne_u32_e32 vcc, v3, v2
	s_and_saveexec_b64 s[6:7], vcc
	s_xor_b64 s[6:7], exec, s[6:7]
	s_cbranch_execz .LBB0_358
	s_waitcnt lgkmcnt(0)
	v_mov_b32_e32 v0, 0x7100
	global_load_dword v0, v0, s[40:41] offset:1024 sc1
	s_add_u32 s16, s40, 0x7500
	s_addc_u32 s17, s41, 0
	s_waitcnt vmcnt(0)
	v_cmp_eq_u32_e32 vcc, v0, v1
	s_and_saveexec_b64 s[8:9], vcc
	s_cbranch_execz .LBB0_357
	s_add_u32 s10, s40, 0x4200
	s_addc_u32 s11, s41, 0
	s_mov_b32 s54, 1
	s_mov_b64 s[36:37], 0
	v_mov_b32_e32 v0, 0
	s_branch .LBB0_348

.LBB0_481:
	s_or_b64 exec, exec, s[16:17]
	v_cvt_f32_u32_e32 v4, v2
	s_waitcnt vmcnt(0)
	v_readfirstlane_b32 s6, v3
	v_sub_u32_e32 v3, 0, v2
	v_rcp_iflag_f32_e32 v4, v4
	v_add_u32_e32 v5, s6, v1
	v_mul_f32_e32 v4, 0x4f7ffffe, v4
	v_cvt_u32_f32_e32 v4, v4
	v_mul_lo_u32 v1, v3, v4
	v_mul_hi_u32 v1, v4, v1
	v_add_u32_e32 v1, v4, v1
	v_mul_hi_u32 v1, v5, v1
	v_mul_lo_u32 v3, v1, v2
	v_sub_u32_e32 v3, v5, v3
	v_add_u32_e32 v4, 1, v1
	v_cmp_ge_u32_e32 vcc, v3, v2
	s_nop 1
	v_cndmask_b32_e32 v1, v1, v4, vcc
	v_sub_u32_e32 v4, v3, v2
	v_cndmask_b32_e32 v3, v3, v4, vcc
	v_add_u32_e32 v4, 1, v1
	v_cmp_ge_u32_e32 vcc, v3, v2
	v_add_u32_e32 v3, 1, v5
	s_nop 0
	v_cndmask_b32_e32 v1, v1, v4, vcc
	v_mul_lo_u32 v4, v2, v1
	v_add_u32_e32 v2, v4, v2
	v_cmp_ne_u32_e32 vcc, v3, v2
	s_and_saveexec_b64 s[6:7], vcc
	s_xor_b64 s[6:7], exec, s[6:7]
	s_cbranch_execz .LBB0_495
	s_waitcnt lgkmcnt(0)
	v_mov_b32_e32 v0, 0x7100
	global_load_dword v0, v0, s[40:41] offset:1024 sc1
	s_add_u32 s44, s40, 0x7500
	s_addc_u32 s45, s41, 0
	s_waitcnt vmcnt(0)
	v_cmp_eq_u32_e32 vcc, v0, v1
	s_and_saveexec_b64 s[16:17], vcc
	s_cbranch_execz .LBB0_494
	s_add_u32 s36, s40, 0x4200
	s_addc_u32 s37, s41, 0
	s_mov_b32 s58, 1
	s_mov_b64 s[46:47], 0
	v_mov_b32_e32 v0, 0
	s_branch .LBB0_485

.LBB0_626:
	s_or_b64 exec, exec, s[10:11]
	v_cvt_f32_u32_e32 v4, v2
	s_waitcnt vmcnt(0)
	v_readfirstlane_b32 s8, v3
	v_sub_u32_e32 v3, 0, v2
	v_rcp_iflag_f32_e32 v4, v4
	v_add_u32_e32 v5, s8, v1
	v_mul_f32_e32 v4, 0x4f7ffffe, v4
	v_cvt_u32_f32_e32 v4, v4
	v_mul_lo_u32 v1, v3, v4
	v_mul_hi_u32 v1, v4, v1
	v_add_u32_e32 v1, v4, v1
	v_mul_hi_u32 v1, v5, v1
	v_mul_lo_u32 v3, v1, v2
	v_sub_u32_e32 v3, v5, v3
	v_add_u32_e32 v4, 1, v1
	v_cmp_ge_u32_e32 vcc, v3, v2
	s_nop 1
	v_cndmask_b32_e32 v1, v1, v4, vcc
	v_sub_u32_e32 v4, v3, v2
	v_cndmask_b32_e32 v3, v3, v4, vcc
	v_add_u32_e32 v4, 1, v1
	v_cmp_ge_u32_e32 vcc, v3, v2
	v_add_u32_e32 v3, 1, v5
	s_nop 0
	v_cndmask_b32_e32 v1, v1, v4, vcc
	v_mul_lo_u32 v4, v2, v1
	v_add_u32_e32 v2, v4, v2
	v_cmp_ne_u32_e32 vcc, v3, v2
	s_and_saveexec_b64 s[8:9], vcc
	s_xor_b64 s[8:9], exec, s[8:9]
	s_cbranch_execz .LBB0_640
	s_waitcnt lgkmcnt(0)
	v_mov_b32_e32 v0, 0x7100
	global_load_dword v0, v0, s[40:41] offset:1024 sc1
	s_add_u32 s16, s40, 0x7500
	s_addc_u32 s17, s41, 0
	s_waitcnt vmcnt(0)
	v_cmp_eq_u32_e32 vcc, v0, v1
	s_and_saveexec_b64 s[10:11], vcc
	s_cbranch_execz .LBB0_639
	s_add_u32 s12, s40, 0x4200
	s_addc_u32 s13, s41, 0
	s_mov_b32 s54, 1
	s_mov_b64 s[36:37], 0
	v_mov_b32_e32 v0, 0
	s_branch .LBB0_630

.LBB0_681:
	s_or_b64 exec, exec, s[12:13]
	v_cvt_f32_u32_e32 v4, v2
	s_waitcnt vmcnt(0)
	v_readfirstlane_b32 s10, v3
	v_sub_u32_e32 v3, 0, v2
	v_rcp_iflag_f32_e32 v4, v4
	v_add_u32_e32 v5, s10, v1
	v_mul_f32_e32 v4, 0x4f7ffffe, v4
	v_cvt_u32_f32_e32 v4, v4
	v_mul_lo_u32 v1, v3, v4
	v_mul_hi_u32 v1, v4, v1
	v_add_u32_e32 v1, v4, v1
	v_mul_hi_u32 v1, v5, v1
	v_mul_lo_u32 v3, v1, v2
	v_sub_u32_e32 v3, v5, v3
	v_add_u32_e32 v4, 1, v1
	v_cmp_ge_u32_e32 vcc, v3, v2
	s_nop 1
	v_cndmask_b32_e32 v1, v1, v4, vcc
	v_sub_u32_e32 v4, v3, v2
	v_cndmask_b32_e32 v3, v3, v4, vcc
	v_add_u32_e32 v4, 1, v1
	v_cmp_ge_u32_e32 vcc, v3, v2
	v_add_u32_e32 v3, 1, v5
	s_nop 0
	v_cndmask_b32_e32 v1, v1, v4, vcc
	v_mul_lo_u32 v4, v2, v1
	v_add_u32_e32 v2, v4, v2
	v_cmp_ne_u32_e32 vcc, v3, v2
	s_and_saveexec_b64 s[10:11], vcc
	s_xor_b64 s[10:11], exec, s[10:11]
	s_cbranch_execz .LBB0_695
	s_waitcnt lgkmcnt(0)
	v_mov_b32_e32 v0, 0x7100
	global_load_dword v0, v0, s[40:41] offset:1024 sc1
	s_add_u32 s30, s40, 0x7500
	s_addc_u32 s31, s41, 0
	s_waitcnt vmcnt(0)
	v_cmp_eq_u32_e32 vcc, v0, v1
	s_and_saveexec_b64 s[12:13], vcc
	s_cbranch_execz .LBB0_694
	s_add_u32 s16, s40, 0x4200
	s_addc_u32 s17, s41, 0
	s_mov_b32 s54, 1
	s_mov_b64 s[36:37], 0
	v_mov_b32_e32 v0, 0
	s_branch .LBB0_685

.LBB0_749:
	s_or_b64 exec, exec, s[16:17]
	v_cvt_f32_u32_e32 v4, v2
	s_waitcnt vmcnt(0)
	v_readfirstlane_b32 s12, v3
	v_sub_u32_e32 v3, 0, v2
	v_rcp_iflag_f32_e32 v4, v4
	v_add_u32_e32 v5, s12, v1
	v_mul_f32_e32 v4, 0x4f7ffffe, v4
	v_cvt_u32_f32_e32 v4, v4
	v_mul_lo_u32 v1, v3, v4
	v_mul_hi_u32 v1, v4, v1
	v_add_u32_e32 v1, v4, v1
	v_mul_hi_u32 v1, v5, v1
	v_mul_lo_u32 v3, v1, v2
	v_sub_u32_e32 v3, v5, v3
	v_add_u32_e32 v4, 1, v1
	v_cmp_ge_u32_e32 vcc, v3, v2
	s_nop 1
	v_cndmask_b32_e32 v1, v1, v4, vcc
	v_sub_u32_e32 v4, v3, v2
	v_cndmask_b32_e32 v3, v3, v4, vcc
	v_add_u32_e32 v4, 1, v1
	v_cmp_ge_u32_e32 vcc, v3, v2
	v_add_u32_e32 v3, 1, v5
	s_nop 0
	v_cndmask_b32_e32 v1, v1, v4, vcc
	v_mul_lo_u32 v4, v2, v1
	v_add_u32_e32 v2, v4, v2
	v_cmp_ne_u32_e32 vcc, v3, v2
	s_and_saveexec_b64 s[12:13], vcc
	s_xor_b64 s[12:13], exec, s[12:13]
	s_cbranch_execz .LBB0_763
	s_waitcnt lgkmcnt(0)
	v_mov_b32_e32 v0, 0x7100
	global_load_dword v0, v0, s[40:41] offset:1024 sc1
	s_add_u32 s30, s40, 0x7500
	s_addc_u32 s31, s41, 0
	s_waitcnt vmcnt(0)
	v_cmp_eq_u32_e32 vcc, v0, v1
	s_and_saveexec_b64 s[16:17], vcc
	s_cbranch_execz .LBB0_762
	s_add_u32 s18, s40, 0x4200
	s_addc_u32 s19, s41, 0
	s_mov_b32 s54, 1
	s_mov_b64 s[36:37], 0
	v_mov_b32_e32 v0, 0
	s_branch .LBB0_753

.LBB0_976:
	s_or_b64 exec, exec, s[16:17]
	v_cvt_f32_u32_e32 v4, v2
	s_waitcnt vmcnt(0)
	v_readfirstlane_b32 s12, v3
	v_sub_u32_e32 v3, 0, v2
	v_rcp_iflag_f32_e32 v4, v4
	v_add_u32_e32 v5, s12, v1
	v_mul_f32_e32 v4, 0x4f7ffffe, v4
	v_cvt_u32_f32_e32 v4, v4
	v_mul_lo_u32 v1, v3, v4
	v_mul_hi_u32 v1, v4, v1
	v_add_u32_e32 v1, v4, v1
	v_mul_hi_u32 v1, v5, v1
	v_mul_lo_u32 v3, v1, v2
	v_sub_u32_e32 v3, v5, v3
	v_add_u32_e32 v4, 1, v1
	v_cmp_ge_u32_e32 vcc, v3, v2
	s_nop 1
	v_cndmask_b32_e32 v1, v1, v4, vcc
	v_sub_u32_e32 v4, v3, v2
	v_cndmask_b32_e32 v3, v3, v4, vcc
	v_add_u32_e32 v4, 1, v1
	v_cmp_ge_u32_e32 vcc, v3, v2
	v_add_u32_e32 v3, 1, v5
	s_nop 0
	v_cndmask_b32_e32 v1, v1, v4, vcc
	v_mul_lo_u32 v4, v2, v1
	v_add_u32_e32 v2, v4, v2
	v_cmp_ne_u32_e32 vcc, v3, v2
	s_and_saveexec_b64 s[12:13], vcc
	s_xor_b64 s[12:13], exec, s[12:13]
	s_cbranch_execz .LBB0_990
	s_waitcnt lgkmcnt(0)
	v_mov_b32_e32 v0, 0x7100
	global_load_dword v0, v0, s[40:41] offset:1024 sc1
	s_add_u32 s36, s40, 0x7500
	s_addc_u32 s37, s41, 0
	s_waitcnt vmcnt(0)
	v_cmp_eq_u32_e32 vcc, v0, v1
	s_and_saveexec_b64 s[16:17], vcc
	s_cbranch_execz .LBB0_989
	s_add_u32 s18, s40, 0x4200
	s_addc_u32 s19, s41, 0
	s_mov_b32 s56, 1
	s_mov_b64 s[44:45], 0
	v_mov_b32_e32 v0, 0
	s_branch .LBB0_980

.LBB0_1260:
	s_or_b64 exec, exec, s[16:17]
	v_cvt_f32_u32_e32 v4, v2
	s_waitcnt vmcnt(0)
	v_readfirstlane_b32 s12, v3
	v_sub_u32_e32 v3, 0, v2
	v_rcp_iflag_f32_e32 v4, v4
	v_add_u32_e32 v5, s12, v1
	v_mul_f32_e32 v4, 0x4f7ffffe, v4
	v_cvt_u32_f32_e32 v4, v4
	v_mul_lo_u32 v1, v3, v4
	v_mul_hi_u32 v1, v4, v1
	v_add_u32_e32 v1, v4, v1
	v_mul_hi_u32 v1, v5, v1
	v_mul_lo_u32 v3, v1, v2
	v_sub_u32_e32 v3, v5, v3
	v_add_u32_e32 v4, 1, v1
	v_cmp_ge_u32_e32 vcc, v3, v2
	s_nop 1
	v_cndmask_b32_e32 v1, v1, v4, vcc
	v_sub_u32_e32 v4, v3, v2
	v_cndmask_b32_e32 v3, v3, v4, vcc
	v_add_u32_e32 v4, 1, v1
	v_cmp_ge_u32_e32 vcc, v3, v2
	v_add_u32_e32 v3, 1, v5
	s_nop 0
	v_cndmask_b32_e32 v1, v1, v4, vcc
	v_mul_lo_u32 v4, v2, v1
	v_add_u32_e32 v2, v4, v2
	v_cmp_ne_u32_e32 vcc, v3, v2
	s_and_saveexec_b64 s[12:13], vcc
	s_xor_b64 s[12:13], exec, s[12:13]
	s_cbranch_execz .LBB0_1274
	s_waitcnt lgkmcnt(0)
	v_mov_b32_e32 v0, 0x7100
	global_load_dword v0, v0, s[40:41] offset:1024 sc1
	s_add_u32 s30, s40, 0x7500
	s_addc_u32 s31, s41, 0
	s_waitcnt vmcnt(0)
	v_cmp_eq_u32_e32 vcc, v0, v1
	s_and_saveexec_b64 s[16:17], vcc
	s_cbranch_execz .LBB0_1273
	s_add_u32 s18, s40, 0x4200
	s_addc_u32 s19, s41, 0
	s_mov_b32 s52, 1
	s_mov_b64 s[36:37], 0
	v_mov_b32_e32 v0, 0
	s_branch .LBB0_1264

.LBB0_1459:
	s_or_b64 exec, exec, s[12:13]
	v_cvt_f32_u32_e32 v4, v2
	s_waitcnt vmcnt(0)
	v_readfirstlane_b32 s10, v3
	v_sub_u32_e32 v3, 0, v2
	v_rcp_iflag_f32_e32 v4, v4
	v_add_u32_e32 v5, s10, v1
	v_mul_f32_e32 v4, 0x4f7ffffe, v4
	v_cvt_u32_f32_e32 v4, v4
	v_mul_lo_u32 v1, v3, v4
	v_mul_hi_u32 v1, v4, v1
	v_add_u32_e32 v1, v4, v1
	v_mul_hi_u32 v1, v5, v1
	v_mul_lo_u32 v3, v1, v2
	v_sub_u32_e32 v3, v5, v3
	v_add_u32_e32 v4, 1, v1
	v_cmp_ge_u32_e32 vcc, v3, v2
	s_nop 1
	v_cndmask_b32_e32 v1, v1, v4, vcc
	v_sub_u32_e32 v4, v3, v2
	v_cndmask_b32_e32 v3, v3, v4, vcc
	v_add_u32_e32 v4, 1, v1
	v_cmp_ge_u32_e32 vcc, v3, v2
	v_add_u32_e32 v3, 1, v5
	s_nop 0
	v_cndmask_b32_e32 v1, v1, v4, vcc
	v_mul_lo_u32 v4, v2, v1
	v_add_u32_e32 v2, v4, v2
	v_cmp_ne_u32_e32 vcc, v3, v2
	s_and_saveexec_b64 s[10:11], vcc
	s_xor_b64 s[10:11], exec, s[10:11]
	s_cbranch_execz .LBB0_1473
	s_waitcnt lgkmcnt(0)
	v_mov_b32_e32 v0, 0x7100
	global_load_dword v0, v0, s[40:41] offset:1024 sc1
	s_add_u32 s18, s40, 0x7500
	s_addc_u32 s19, s41, 0
	s_waitcnt vmcnt(0)
	v_cmp_eq_u32_e32 vcc, v0, v1
	s_and_saveexec_b64 s[12:13], vcc
	s_cbranch_execz .LBB0_1472
	s_add_u32 s16, s40, 0x4200
	s_addc_u32 s17, s41, 0
	s_mov_b32 s50, 1
	s_mov_b64 s[30:31], 0
	v_mov_b32_e32 v0, 0
	s_branch .LBB0_1463

.LBB0_1539:
	s_or_b64 exec, exec, s[8:9]
	v_cvt_f32_u32_e32 v4, v2
	s_waitcnt vmcnt(0)
	v_readfirstlane_b32 s6, v3
	v_sub_u32_e32 v3, 0, v2
	v_rcp_iflag_f32_e32 v4, v4
	v_add_u32_e32 v5, s6, v1
	v_mul_f32_e32 v4, 0x4f7ffffe, v4
	v_cvt_u32_f32_e32 v4, v4
	v_mul_lo_u32 v1, v3, v4
	v_mul_hi_u32 v1, v4, v1
	v_add_u32_e32 v1, v4, v1
	v_mul_hi_u32 v1, v5, v1
	v_mul_lo_u32 v3, v1, v2
	v_sub_u32_e32 v3, v5, v3
	v_add_u32_e32 v4, 1, v1
	v_cmp_ge_u32_e32 vcc, v3, v2
	s_nop 1
	v_cndmask_b32_e32 v1, v1, v4, vcc
	v_sub_u32_e32 v4, v3, v2
	v_cndmask_b32_e32 v3, v3, v4, vcc
	v_add_u32_e32 v4, 1, v1
	v_cmp_ge_u32_e32 vcc, v3, v2
	v_add_u32_e32 v3, 1, v5
	s_nop 0
	v_cndmask_b32_e32 v1, v1, v4, vcc
	v_mul_lo_u32 v4, v2, v1
	v_add_u32_e32 v2, v4, v2
	v_cmp_ne_u32_e32 vcc, v3, v2
	s_and_saveexec_b64 s[6:7], vcc
	s_xor_b64 s[6:7], exec, s[6:7]
	s_cbranch_execz .LBB0_1553
	s_waitcnt lgkmcnt(0)
	v_mov_b32_e32 v0, 0x7100
	global_load_dword v0, v0, s[40:41] offset:1024 sc1
	s_add_u32 s12, s40, 0x7500
	s_addc_u32 s13, s41, 0
	s_waitcnt vmcnt(0)
	v_cmp_eq_u32_e32 vcc, v0, v1
	s_and_saveexec_b64 s[8:9], vcc
	s_cbranch_execz .LBB0_1552
	s_add_u32 s10, s40, 0x4200
	s_addc_u32 s11, s41, 0
	s_mov_b32 s24, 1
	s_mov_b64 s[14:15], 0
	v_mov_b32_e32 v0, 0
	s_branch .LBB0_1543
